# prologue weight transposes: the 32 pre-norm gain values of each 64x64 item are now loaded up front with one wait (was 8 groups of 4 loads, each with a full round-trip wait) in both the QKV and up-proj
# speedup vs baseline: 1.0085x; 1.0021x over previous
; __device__ __forceinline__ void transpose_item(const float* W, int ldw, int col0_src, bf16* WT, int K, int row0_dst, const float* gain, LAS float* scr, int k0, int lane) {
;     float wv[32];
; #pragma unroll
;     for (int i = 0; i < 32; ++i) wv[i] = W[(size_t)(k0 + 2 * i + (lane >> 5)) * ldw + col0_src + (lane & 31)];
; __device__ __forceinline__ void prologue_phase(const Args& a, LAS unsigned char* lds) {
;     ...
;         if (r < 2 * I_QKV1) { const int l = r / I_QKV1; r -= l * I_QKV1; const int nblk = NQKV / 32, kb = r / nblk, nb = r % nblk;
;             transpose_item(a.in[I_WQKV] + (size_t)l * DM * NQKV, NQKV, nb * 32, (bf16*)(ws + WS_WQKV) + (size_t)l * NQKV * DM, DM, nb * 32, a.in[I_NMIX] + (2 * l) * DM, scr, kb * 64, lane); continue; }
.LBB0_17:
	s_andn2_b64 vcc, exec, s[2:3]
	s_cbranch_vccnz .LBB0_43
	s_add_i32 s4, s83, 0xfffef800
	s_cmpk_gt_u32 s4, 0x9ff
	s_cselect_b64 s[48:49], -1, 0
	s_and_b64 s[2:3], s[48:49], exec
	s_cselect_b32 s2, 0xf600, 0
	s_cselect_b32 s3, 0x1400000, 0
	s_cselect_b32 s5, 0x4000, 0
	s_add_i32 s4, s4, s2
	s_sext_i32_i16 s2, s4
	s_mulk_i32 s2, 0x6667
	s_lshr_b32 s42, s2, 31
	s_ashr_i32 s2, s2, 21
	s_add_i32 s2, s2, s42
	s_mul_i32 s42, s2, 0x50
	s_sub_i32 s4, s4, s42
	s_sext_i32_i16 s4, s4
	s_add_u32 s42, s6, s3
	s_addc_u32 s51, s7, 0
	s_lshl_b32 s46, s4, 5
	s_add_u32 s52, s14, s5
	s_addc_u32 s53, s15, 0
	s_ashr_i32 s47, s46, 31
	s_lshl_b32 s50, s2, 6
	s_lshl_b64 s[2:3], s[46:47], 2
	v_or_b32_e32 v24, s50, v4
	s_add_u32 s2, s42, s2
	s_addc_u32 s3, s51, s3
	v_mul_i32_i24_e32 v14, 0xa00, v24
	v_lshl_add_u64 v[10:11], s[2:3], 0, v[6:7]
	v_mul_hi_i32_i24_e32 v13, 0x2800, v24
	v_mul_i32_i24_e32 v12, 0x2800, v24
	v_ashrrev_i32_e32 v15, 31, v14
	v_lshl_add_u64 v[12:13], v[10:11], 0, v[12:13]
	v_lshl_add_u64 v[10:11], v[14:15], 2, v[10:11]
	s_movk_i32 s2, 0x5000
	v_add_co_u32_e32 v14, vcc, s2, v10
	s_mov_b32 s2, 0xf000
	s_nop 0
	v_addc_co_u32_e32 v15, vcc, 0, v11, vcc
	v_add_co_u32_e32 v16, vcc, s68, v10
	v_cndmask_b32_e64 v25, 0, 1, s[34:35]
	s_nop 0
	v_addc_co_u32_e32 v17, vcc, 0, v11, vcc
	v_add_co_u32_e32 v18, vcc, s2, v10
	s_mov_b32 s2, 0x19000
	s_nop 0
	v_addc_co_u32_e32 v19, vcc, 0, v11, vcc
	v_add_co_u32_e32 v20, vcc, s72, v10
	v_cmp_ne_u32_e64 s[4:5], 1, v25
	s_nop 0
	v_addc_co_u32_e32 v21, vcc, 0, v11, vcc
	v_add_co_u32_e32 v22, vcc, s2, v10
	s_nop 1
	v_addc_co_u32_e32 v23, vcc, 0, v11, vcc
	v_add_co_u32_e32 v52, vcc, s75, v10
	s_nop 1
	v_addc_co_u32_e32 v53, vcc, 0, v11, vcc
	v_add_co_u32_e32 v54, vcc, s84, v10
	s_nop 1
	v_addc_co_u32_e32 v55, vcc, 0, v11, vcc
	global_load_dword v64, v[12:13], off
	global_load_dword v65, v[14:15], off
	global_load_dword v26, v[16:17], off
	global_load_dword v27, v[18:19], off
	global_load_dword v62, v[20:21], off
	global_load_dword v63, v[22:23], off
	s_nop 0
	global_load_dword v22, v[52:53], off
	global_load_dword v23, v[54:55], off
	v_add_co_u32_e32 v12, vcc, s76, v10
	s_nop 1
	v_addc_co_u32_e32 v13, vcc, 0, v11, vcc
	v_add_co_u32_e32 v14, vcc, s85, v10
	s_nop 1
	v_addc_co_u32_e32 v15, vcc, 0, v11, vcc
	v_add_co_u32_e32 v16, vcc, s86, v10
	s_nop 1
	v_addc_co_u32_e32 v17, vcc, 0, v11, vcc
	v_add_co_u32_e32 v18, vcc, s87, v10
	s_nop 1
	v_addc_co_u32_e32 v19, vcc, 0, v11, vcc
	v_add_co_u32_e32 v52, vcc, s77, v10
	s_nop 1
	v_addc_co_u32_e32 v53, vcc, 0, v11, vcc
	v_add_co_u32_e32 v54, vcc, s88, v10
	s_nop 1
	v_addc_co_u32_e32 v55, vcc, 0, v11, vcc
	v_add_co_u32_e32 v56, vcc, s89, v10
	s_nop 1
	v_addc_co_u32_e32 v57, vcc, 0, v11, vcc
	v_add_co_u32_e32 v66, vcc, s90, v10
	s_nop 1
	v_addc_co_u32_e32 v67, vcc, 0, v11, vcc
	global_load_dword v60, v[12:13], off
	global_load_dword v61, v[14:15], off
	global_load_dword v20, v[16:17], off
	global_load_dword v21, v[18:19], off
	global_load_dword v58, v[52:53], off
	global_load_dword v59, v[54:55], off
	s_nop 0
	global_load_dword v18, v[56:57], off
	global_load_dword v19, v[66:67], off
	v_add_co_u32_e32 v12, vcc, s78, v10
	s_nop 1
	v_addc_co_u32_e32 v13, vcc, 0, v11, vcc
	v_add_co_u32_e32 v14, vcc, s91, v10
	s_nop 1
	v_addc_co_u32_e32 v15, vcc, 0, v11, vcc
	v_add_co_u32_e32 v16, vcc, s92, v10
	s_nop 1
	v_addc_co_u32_e32 v17, vcc, 0, v11, vcc
	v_add_co_u32_e32 v52, vcc, s93, v10
	s_nop 1
	v_addc_co_u32_e32 v53, vcc, 0, v11, vcc
	v_add_co_u32_e32 v54, vcc, s79, v10
	s_nop 1
	v_addc_co_u32_e32 v55, vcc, 0, v11, vcc
	v_add_co_u32_e32 v66, vcc, s94, v10
	s_nop 1
	v_addc_co_u32_e32 v67, vcc, 0, v11, vcc
	v_add_co_u32_e32 v68, vcc, s95, v10
	s_nop 1
	v_addc_co_u32_e32 v69, vcc, 0, v11, vcc
	v_add_co_u32_e32 v70, vcc, s96, v10
	s_nop 1
	v_addc_co_u32_e32 v71, vcc, 0, v11, vcc
	global_load_dword v56, v[12:13], off
	global_load_dword v57, v[14:15], off
	s_nop 0
	global_load_dword v16, v[16:17], off
	s_nop 0
	global_load_dword v17, v[52:53], off
	s_nop 0
	global_load_dword v53, v[54:55], off
	s_nop 0
	global_load_dword v55, v[66:67], off
	global_load_dword v14, v[68:69], off
	global_load_dword v15, v[70:71], off
	v_add_co_u32_e32 v12, vcc, s82, v10
	s_nop 1
	v_addc_co_u32_e32 v13, vcc, 0, v11, vcc
	v_add_co_u32_e32 v66, vcc, s97, v10
	s_nop 1
	v_addc_co_u32_e32 v67, vcc, 0, v11, vcc
	v_add_co_u32_e32 v68, vcc, s0, v10
	s_nop 1
	v_addc_co_u32_e32 v69, vcc, 0, v11, vcc
	v_add_co_u32_e32 v70, vcc, s80, v10
	s_nop 1
	v_addc_co_u32_e32 v71, vcc, 0, v11, vcc
	v_add_co_u32_e32 v72, vcc, s81, v10
	s_nop 1
	v_addc_co_u32_e32 v73, vcc, 0, v11, vcc
	v_add_co_u32_e32 v74, vcc, 0x91000, v10
	s_nop 1
	v_addc_co_u32_e32 v75, vcc, 0, v11, vcc
	v_add_co_u32_e32 v76, vcc, 0x96000, v10
	s_nop 1
	v_addc_co_u32_e32 v77, vcc, 0, v11, vcc
	v_add_co_u32_e32 v78, vcc, 0x9b000, v10
	s_nop 1
	v_addc_co_u32_e32 v79, vcc, 0, v11, vcc
	global_load_dword v52, v[12:13], off
	global_load_dword v54, v[66:67], off
	s_nop 0
	global_load_dword v12, v[68:69], off
	global_load_dword v13, v[70:71], off
	global_load_dword v9, v[72:73], off
	global_load_dword v51, v[74:75], off
	global_load_dword v10, v[76:77], off
	global_load_dword v11, v[78:79], off
	s_andn2_b64 vcc, exec, s[34:35]
	s_cbranch_vccnz .LBB0_79
; __device__ __forceinline__ void transpose_item(const float* W, int ldw, int col0_src, bf16* WT, int K, int row0_dst, const float* gain, LAS float* scr, int k0, int lane) {
;     ...
; #pragma unroll
;     for (int i = 0; i < 32; ++i) { const int kk = 2 * i + (lane >> 5); float v = wv[i]; if (gain) v *= gain[k0 + kk]; scr[kk * 33 + (lane & 31)] = v; }
	v_ashrrev_i32_e32 v25, 31, v24
	s_ashr_i32 s51, s50, 31
	v_lshl_add_u64 v[66:67], s[50:51], 0, v[4:5]
	v_lshl_add_u64 v[66:67], v[66:67], 2, s[52:53]
	global_load_dword v184, v[66:67], off
	global_load_dword v185, v[66:67], off offset:8
	global_load_dword v186, v[66:67], off offset:16
	global_load_dword v187, v[66:67], off offset:24
	global_load_dword v188, v[66:67], off offset:32
	global_load_dword v189, v[66:67], off offset:40
	global_load_dword v190, v[66:67], off offset:48
	global_load_dword v191, v[66:67], off offset:56
	global_load_dword v192, v[66:67], off offset:64
	global_load_dword v193, v[66:67], off offset:72
	global_load_dword v194, v[66:67], off offset:80
	global_load_dword v195, v[66:67], off offset:88
	global_load_dword v196, v[66:67], off offset:96
	global_load_dword v197, v[66:67], off offset:104
	global_load_dword v198, v[66:67], off offset:112
	global_load_dword v199, v[66:67], off offset:120
	global_load_dword v200, v[66:67], off offset:128
	global_load_dword v201, v[66:67], off offset:136
	global_load_dword v202, v[66:67], off offset:144
	global_load_dword v203, v[66:67], off offset:152
	global_load_dword v204, v[66:67], off offset:160
	global_load_dword v205, v[66:67], off offset:168
	global_load_dword v206, v[66:67], off offset:176
	global_load_dword v207, v[66:67], off offset:184
	global_load_dword v208, v[66:67], off offset:192
	global_load_dword v209, v[66:67], off offset:200
	global_load_dword v210, v[66:67], off offset:208
	global_load_dword v211, v[66:67], off offset:216
	global_load_dword v212, v[66:67], off offset:224
	global_load_dword v213, v[66:67], off offset:232
	global_load_dword v214, v[66:67], off offset:240
	global_load_dword v215, v[66:67], off offset:248
	s_waitcnt vmcnt(0)
	s_nop 0
	v_mul_f32_e32 v66, v64, v184
	v_mul_f32_e32 v67, v65, v185
	ds_write2_b32 v41, v66, v67 offset1:66
	v_pk_mul_f32 v[24:25], v[26:27], v[186:187]
	s_cbranch_execnz .LBB0_21

; __device__ __forceinline__ void transpose_item(const float* W, int ldw, int col0_src, bf16* WT, int K, int row0_dst, const float* gain, LAS float* scr, int k0, int lane) {
;     ...
; #pragma unroll
;     for (int i = 0; i < 32; ++i) { const int kk = 2 * i + (lane >> 5); float v = wv[i]; if (gain) v *= gain[k0 + kk]; scr[kk * 33 + (lane & 31)] = v; }
.LBB0_21:
	s_waitcnt vmcnt(29)
	v_add_u32_e32 v26, v28, v29
	s_and_b64 vcc, exec, s[4:5]
	ds_write2_b32 v26, v24, v25 offset1:66
	s_cbranch_vccnz .LBB0_80
	s_ashr_i32 s51, s50, 31
	v_add_u32_e32 v66, v28, v30
	v_mul_f32_e32 v64, v62, v188
	v_mul_f32_e32 v65, v63, v189
	ds_write2_b32 v66, v64, v65 offset1:66
	v_pk_mul_f32 v[24:25], v[22:23], v[190:191]
	s_cbranch_execnz .LBB0_24

; __device__ __forceinline__ void transpose_item(const float* W, int ldw, int col0_src, bf16* WT, int K, int row0_dst, const float* gain, LAS float* scr, int k0, int lane) {
;     ...
; #pragma unroll
;     for (int i = 0; i < 32; ++i) { const int kk = 2 * i + (lane >> 5); float v = wv[i]; if (gain) v *= gain[k0 + kk]; scr[kk * 33 + (lane & 31)] = v; }
.LBB0_24:
	s_and_b64 vcc, exec, s[4:5]
	ds_write2_b32 v42, v24, v25 offset1:66
	s_cbranch_vccnz .LBB0_81
	s_ashr_i32 s51, s50, 31
	s_waitcnt vmcnt(24)
	v_add_u32_e32 v62, v28, v31
	v_mul_f32_e32 v26, v60, v192
	v_mul_f32_e32 v27, v61, v193
	ds_write2_b32 v62, v26, v27 offset1:66
	v_pk_mul_f32 v[22:23], v[20:21], v[194:195]
	s_cbranch_execnz .LBB0_27

; __device__ __forceinline__ void transpose_item(const float* W, int ldw, int col0_src, bf16* WT, int K, int row0_dst, const float* gain, LAS float* scr, int k0, int lane) {
;     ...
; #pragma unroll
;     for (int i = 0; i < 32; ++i) { const int kk = 2 * i + (lane >> 5); float v = wv[i]; if (gain) v *= gain[k0 + kk]; scr[kk * 33 + (lane & 31)] = v; }
.LBB0_27:
	s_waitcnt vmcnt(21)
	v_add_u32_e32 v20, v28, v32
	s_and_b64 vcc, exec, s[4:5]
	ds_write2_b32 v20, v22, v23 offset1:66
	s_cbranch_vccnz .LBB0_82
	s_ashr_i32 s51, s50, 31
	s_waitcnt vmcnt(20)
	v_mul_f32_e32 v24, v58, v196
	v_mul_f32_e32 v25, v59, v197
	ds_write2_b32 v43, v24, v25 offset1:66
	v_pk_mul_f32 v[20:21], v[18:19], v[198:199]
	s_cbranch_execnz .LBB0_30

; __device__ __forceinline__ void transpose_item(const float* W, int ldw, int col0_src, bf16* WT, int K, int row0_dst, const float* gain, LAS float* scr, int k0, int lane) {
;     ...
; #pragma unroll
;     for (int i = 0; i < 32; ++i) { const int kk = 2 * i + (lane >> 5); float v = wv[i]; if (gain) v *= gain[k0 + kk]; scr[kk * 33 + (lane & 31)] = v; }
.LBB0_30:
	s_waitcnt vmcnt(17)
	v_add_u32_e32 v18, v28, v33
	s_and_b64 vcc, exec, s[4:5]
	ds_write2_b32 v18, v20, v21 offset1:66
	s_cbranch_vccnz .LBB0_83
	s_ashr_i32 s51, s50, 31
	s_waitcnt vmcnt(16)
	v_add_u32_e32 v24, v28, v34
	v_mul_f32_e32 v22, v56, v200
	v_mul_f32_e32 v23, v57, v201
	ds_write2_b32 v24, v22, v23 offset1:66
	v_pk_mul_f32 v[18:19], v[16:17], v[202:203]
	s_cbranch_execnz .LBB0_33

; __device__ __forceinline__ void transpose_item(const float* W, int ldw, int col0_src, bf16* WT, int K, int row0_dst, const float* gain, LAS float* scr, int k0, int lane) {
;     ...
; #pragma unroll
;     for (int i = 0; i < 32; ++i) { const int kk = 2 * i + (lane >> 5); float v = wv[i]; if (gain) v *= gain[k0 + kk]; scr[kk * 33 + (lane & 31)] = v; }
.LBB0_33:
	s_and_b64 vcc, exec, s[4:5]
	s_waitcnt vmcnt(16)
	ds_write2_b32 v44, v18, v19 offset1:66
	s_cbranch_vccnz .LBB0_84
	s_ashr_i32 s51, s50, 31
	s_waitcnt vmcnt(12)
	v_add_u32_e32 v22, v28, v35
	v_mul_f32_e32 v20, v53, v204
	v_mul_f32_e32 v21, v55, v205
	ds_write2_b32 v22, v20, v21 offset1:66
	v_pk_mul_f32 v[16:17], v[14:15], v[206:207]
	s_cbranch_execnz .LBB0_36

; __device__ __forceinline__ void transpose_item(const float* W, int ldw, int col0_src, bf16* WT, int K, int row0_dst, const float* gain, LAS float* scr, int k0, int lane) {
;     ...
; #pragma unroll
;     for (int i = 0; i < 32; ++i) { const int kk = 2 * i + (lane >> 5); float v = wv[i]; if (gain) v *= gain[k0 + kk]; scr[kk * 33 + (lane & 31)] = v; }
.LBB0_36:
	v_add_u32_e32 v18, v28, v35
	s_waitcnt vmcnt(12)
	ds_write2_b32 v18, v16, v17 offset0:132 offset1:198
	s_and_b64 vcc, exec, s[4:5]
	v_add_u32_e32 v16, 0x400, v18
	s_cbranch_vccnz .LBB0_85
	s_ashr_i32 s51, s50, 31
	s_waitcnt vmcnt(8)
	v_mul_f32_e32 v17, v52, v208
	v_mul_f32_e32 v19, v54, v209
	ds_write2_b32 v16, v17, v19 offset0:8 offset1:74
	v_pk_mul_f32 v[14:15], v[12:13], v[210:211]
	s_cbranch_execnz .LBB0_39

; __device__ __forceinline__ void transpose_item(const float* W, int ldw, int col0_src, bf16* WT, int K, int row0_dst, const float* gain, LAS float* scr, int k0, int lane) {
;     ...
; #pragma unroll
;     for (int i = 0; i < 32; ++i) { const int kk = 2 * i + (lane >> 5); float v = wv[i]; if (gain) v *= gain[k0 + kk]; scr[kk * 33 + (lane & 31)] = v; }
.LBB0_39:
	s_waitcnt vmcnt(8)
	ds_write2_b32 v16, v14, v15 offset0:140 offset1:206
	s_and_b64 vcc, exec, s[4:5]
	v_add_u32_e32 v14, 0x800, v18
	s_cbranch_vccnz .LBB0_86
	s_ashr_i32 s51, s50, 31
	s_waitcnt vmcnt(4)
	v_mul_f32_e32 v15, v9, v212
	v_mul_f32_e32 v18, v51, v213
	ds_write2_b32 v14, v15, v18 offset0:16 offset1:82
	v_pk_mul_f32 v[12:13], v[10:11], v[214:215]
	s_cbranch_execnz .LBB0_42

; __device__ __forceinline__ void transpose_item(const float* W, int ldw, int col0_src, bf16* WT, int K, int row0_dst, const float* gain, LAS float* scr, int k0, int lane) {
;     ...
;     for (int i = 0; i < 32; ++i) wv[i] = W[(size_t)(k0 + 2 * i + (lane >> 5)) * ldw + col0_src + (lane & 31)];
; #pragma unroll
;     for (int i = 0; i < 32; ++i) { const int kk = 2 * i + (lane >> 5); float v = wv[i]; if (gain) v *= gain[k0 + kk]; scr[kk * 33 + (lane & 31)] = v; }
; __device__ __forceinline__ void prologue_phase(const Args& a, LAS unsigned char* lds) {
;     ...
;         if (r < 4 * I_UP1) { const int l = r / I_UP1; r -= l * I_UP1; const int nblk = NUP / 32, kb = r / nblk, nb = r % nblk, n0 = nb * 32;
;             const int src = ((n0 >> 7) & 1) * DFF + (n0 >> 8) * 128 + (n0 & 127);
;             transpose_item(a.in[I_WUP] + (size_t)l * DM * NUP, NUP, src, (bf16*)(ws + WS_WUP) + (size_t)l * NUP * DM, DM, n0, a.in[I_NFFN] + l * DM, scr, kb * 64, lane); continue; }
.LBB0_47:
	s_andn2_b64 vcc, exec, s[2:3]
	s_cbranch_vccnz .LBB0_8
	s_mul_hi_i32 s2, s83, 0x2e8ba2e9
	s_lshr_b32 s3, s2, 31
	s_ashr_i32 s50, s2, 11
	s_add_i32 s50, s50, s3
	s_mul_i32 s2, s50, 0xffffd400
	s_add_i32 s2, s83, s2
	s_mul_hi_i32 s3, s2, 0x2e8ba2e9
	s_lshr_b32 s4, s3, 31
	s_ashr_i32 s3, s3, 6
	s_add_i32 s3, s3, s4
	s_mul_i32 s4, s3, 0x160
	s_sub_i32 s2, s2, s4
	s_lshl_b32 s42, s2, 5
	s_bfe_i32 s4, s2, 0x10002
	s_lshl_b32 s2, s2, 4
	s_and_b32 s4, s4, 0x1600
	s_and_b32 s2, s2, 0xffffff80
	s_add_i32 s4, s4, s2
	s_and_b32 s2, s42, 0x60
	s_or_b32 s2, s4, s2
	s_mul_i32 s5, s50, 0x5800000
	s_mul_hi_i32 s4, s50, 0x5800000
	s_add_u32 s47, s28, s5
	s_addc_u32 s51, s29, s4
	s_lshl_b32 s4, s50, 11
	s_ashr_i32 s5, s4, 31
	s_lshl_b64 s[4:5], s[4:5], 2
	s_add_u32 s48, s16, s4
	s_addc_u32 s49, s17, s5
	s_lshl_b32 s46, s3, 6
	s_ashr_i32 s3, s2, 31
	s_lshl_b64 s[2:3], s[2:3], 2
	s_add_u32 s2, s47, s2
	v_or_b32_e32 v26, s46, v4
	s_addc_u32 s3, s51, s3
	v_lshl_add_u64 v[10:11], s[2:3], 0, v[6:7]
	v_or_b32_e32 v9, 2, v26
	v_mad_i64_i32 v[14:15], s[2:3], v9, s69, v[10:11]
	v_or_b32_e32 v9, 4, v26
	v_mad_i64_i32 v[16:17], s[2:3], v9, s69, v[10:11]
	v_or_b32_e32 v9, 6, v26
	v_mad_i64_i32 v[18:19], s[2:3], v9, s69, v[10:11]
	v_or_b32_e32 v9, 8, v26
	v_mad_i64_i32 v[20:21], s[2:3], v9, s69, v[10:11]
	v_or_b32_e32 v9, 10, v26
	v_mad_i64_i32 v[22:23], s[2:3], v9, s69, v[10:11]
	v_or_b32_e32 v9, 12, v26
	v_mad_i64_i32 v[52:53], s[2:3], v9, s69, v[10:11]
	v_or_b32_e32 v9, 14, v26
	v_mad_i64_i32 v[12:13], s[2:3], v26, s69, v[10:11]
	v_mad_i64_i32 v[54:55], s[2:3], v9, s69, v[10:11]
	v_or_b32_e32 v9, 16, v26
	global_load_dword v64, v[12:13], off
	global_load_dword v65, v[14:15], off
	global_load_dword v24, v[16:17], off
	global_load_dword v25, v[18:19], off
	global_load_dword v62, v[20:21], off
	global_load_dword v63, v[22:23], off
	s_nop 0
	global_load_dword v22, v[52:53], off
	global_load_dword v23, v[54:55], off
	v_mad_i64_i32 v[12:13], s[2:3], v9, s69, v[10:11]
	v_or_b32_e32 v9, 18, v26
	v_mad_i64_i32 v[14:15], s[2:3], v9, s69, v[10:11]
	v_or_b32_e32 v9, 20, v26
	v_mad_i64_i32 v[16:17], s[2:3], v9, s69, v[10:11]
	v_or_b32_e32 v9, 22, v26
	v_mad_i64_i32 v[18:19], s[2:3], v9, s69, v[10:11]
	v_or_b32_e32 v9, 24, v26
	v_mad_i64_i32 v[52:53], s[2:3], v9, s69, v[10:11]
	v_or_b32_e32 v9, 26, v26
	v_mad_i64_i32 v[54:55], s[2:3], v9, s69, v[10:11]
	v_or_b32_e32 v9, 28, v26
	v_mad_i64_i32 v[56:57], s[2:3], v9, s69, v[10:11]
	v_or_b32_e32 v9, 30, v26
	v_mad_i64_i32 v[66:67], s[2:3], v9, s69, v[10:11]
	v_or_b32_e32 v9, 32, v26
	global_load_dword v60, v[12:13], off
	global_load_dword v61, v[14:15], off
	global_load_dword v20, v[16:17], off
	global_load_dword v21, v[18:19], off
	global_load_dword v58, v[52:53], off
	global_load_dword v59, v[54:55], off
	s_nop 0
	global_load_dword v18, v[56:57], off
	global_load_dword v19, v[66:67], off
	v_mad_i64_i32 v[12:13], s[2:3], v9, s69, v[10:11]
	v_or_b32_e32 v9, 34, v26
	v_mad_i64_i32 v[14:15], s[2:3], v9, s69, v[10:11]
	v_or_b32_e32 v9, 36, v26
	v_mad_i64_i32 v[16:17], s[2:3], v9, s69, v[10:11]
	v_or_b32_e32 v9, 38, v26
	v_mad_i64_i32 v[52:53], s[2:3], v9, s69, v[10:11]
	v_or_b32_e32 v9, 40, v26
	v_mad_i64_i32 v[54:55], s[2:3], v9, s69, v[10:11]
	v_or_b32_e32 v9, 42, v26
	v_mad_i64_i32 v[66:67], s[2:3], v9, s69, v[10:11]
	v_or_b32_e32 v9, 44, v26
	v_mad_i64_i32 v[68:69], s[2:3], v9, s69, v[10:11]
	v_or_b32_e32 v9, 46, v26
	v_mad_i64_i32 v[70:71], s[2:3], v9, s69, v[10:11]
	v_or_b32_e32 v9, 48, v26
	global_load_dword v56, v[12:13], off
	global_load_dword v57, v[14:15], off
	s_nop 0
	global_load_dword v16, v[16:17], off
	s_nop 0
	global_load_dword v17, v[52:53], off
	s_nop 0
	global_load_dword v54, v[54:55], off
	s_nop 0
	global_load_dword v55, v[66:67], off
	global_load_dword v14, v[68:69], off
	global_load_dword v15, v[70:71], off
	v_mad_i64_i32 v[12:13], s[2:3], v9, s69, v[10:11]
	v_or_b32_e32 v9, 50, v26
	v_mad_i64_i32 v[66:67], s[2:3], v9, s69, v[10:11]
	v_or_b32_e32 v9, 52, v26
	v_mad_i64_i32 v[68:69], s[2:3], v9, s69, v[10:11]
	v_or_b32_e32 v9, 54, v26
	v_mad_i64_i32 v[70:71], s[2:3], v9, s69, v[10:11]
	v_or_b32_e32 v9, 56, v26
	v_mad_i64_i32 v[72:73], s[2:3], v9, s69, v[10:11]
	v_or_b32_e32 v9, 58, v26
	v_mad_i64_i32 v[74:75], s[2:3], v9, s69, v[10:11]
	v_or_b32_e32 v9, 60, v26
	v_mad_i64_i32 v[76:77], s[2:3], v9, s69, v[10:11]
	v_or_b32_e32 v9, 62, v26
	v_mad_i64_i32 v[78:79], s[2:3], v9, s69, v[10:11]
	global_load_dword v52, v[12:13], off
	global_load_dword v53, v[66:67], off
	s_nop 0
	global_load_dword v12, v[68:69], off
	global_load_dword v13, v[70:71], off
	global_load_dword v9, v[72:73], off
	global_load_dword v51, v[74:75], off
	global_load_dword v10, v[76:77], off
	global_load_dword v11, v[78:79], off
	v_cndmask_b32_e64 v27, 0, 1, s[40:41]
	v_cmp_ne_u32_e64 s[4:5], 1, v27
	s_andn2_b64 vcc, exec, s[40:41]
	s_cbranch_vccnz .LBB0_71
	v_ashrrev_i32_e32 v27, 31, v26
	s_ashr_i32 s47, s46, 31
	v_lshl_add_u64 v[66:67], s[46:47], 0, v[4:5]
	v_lshl_add_u64 v[66:67], v[66:67], 2, s[48:49]
	global_load_dword v184, v[66:67], off
	global_load_dword v185, v[66:67], off offset:8
	global_load_dword v186, v[66:67], off offset:16
	global_load_dword v187, v[66:67], off offset:24
	global_load_dword v188, v[66:67], off offset:32
	global_load_dword v189, v[66:67], off offset:40
	global_load_dword v190, v[66:67], off offset:48
	global_load_dword v191, v[66:67], off offset:56
	global_load_dword v192, v[66:67], off offset:64
	global_load_dword v193, v[66:67], off offset:72
	global_load_dword v194, v[66:67], off offset:80
	global_load_dword v195, v[66:67], off offset:88
	global_load_dword v196, v[66:67], off offset:96
	global_load_dword v197, v[66:67], off offset:104
	global_load_dword v198, v[66:67], off offset:112
	global_load_dword v199, v[66:67], off offset:120
	global_load_dword v200, v[66:67], off offset:128
	global_load_dword v201, v[66:67], off offset:136
	global_load_dword v202, v[66:67], off offset:144
	global_load_dword v203, v[66:67], off offset:152
	global_load_dword v204, v[66:67], off offset:160
	global_load_dword v205, v[66:67], off offset:168
	global_load_dword v206, v[66:67], off offset:176
	global_load_dword v207, v[66:67], off offset:184
	global_load_dword v208, v[66:67], off offset:192
	global_load_dword v209, v[66:67], off offset:200
	global_load_dword v210, v[66:67], off offset:208
	global_load_dword v211, v[66:67], off offset:216
	global_load_dword v212, v[66:67], off offset:224
	global_load_dword v213, v[66:67], off offset:232
	global_load_dword v214, v[66:67], off offset:240
	global_load_dword v215, v[66:67], off offset:248
	s_waitcnt vmcnt(0)
	s_nop 0
	v_mul_f32_e32 v66, v64, v184
	v_mul_f32_e32 v67, v65, v185
	ds_write2_b32 v41, v66, v67 offset1:66
	v_pk_mul_f32 v[26:27], v[24:25], v[186:187]
	s_cbranch_execnz .LBB0_51

; __device__ __forceinline__ void transpose_item(const float* W, int ldw, int col0_src, bf16* WT, int K, int row0_dst, const float* gain, LAS float* scr, int k0, int lane) {
;     ...
; #pragma unroll
;     for (int i = 0; i < 32; ++i) { const int kk = 2 * i + (lane >> 5); float v = wv[i]; if (gain) v *= gain[k0 + kk]; scr[kk * 33 + (lane & 31)] = v; }
.LBB0_51:
	s_waitcnt vmcnt(29)
	v_add_u32_e32 v24, v28, v29
	ds_write2_b32 v24, v26, v27 offset1:66
	s_and_b64 vcc, exec, s[4:5]
	v_add_u32_e32 v26, v28, v30
	s_cbranch_vccnz .LBB0_72
	s_ashr_i32 s47, s46, 31
	s_waitcnt vmcnt(28)
	v_mul_f32_e32 v27, v62, v188
	v_mul_f32_e32 v66, v63, v189
	ds_write2_b32 v26, v27, v66 offset1:66
	v_pk_mul_f32 v[24:25], v[22:23], v[190:191]
	s_cbranch_execnz .LBB0_54

; __device__ __forceinline__ void transpose_item(const float* W, int ldw, int col0_src, bf16* WT, int K, int row0_dst, const float* gain, LAS float* scr, int k0, int lane) {
;     ...
; #pragma unroll
;     for (int i = 0; i < 32; ++i) { const int kk = 2 * i + (lane >> 5); float v = wv[i]; if (gain) v *= gain[k0 + kk]; scr[kk * 33 + (lane & 31)] = v; }
.LBB0_54:
	s_waitcnt vmcnt(28)
	ds_write2_b32 v42, v24, v25 offset1:66
	s_and_b64 vcc, exec, s[4:5]
	v_add_u32_e32 v24, v28, v31
	s_cbranch_vccnz .LBB0_73
	s_ashr_i32 s47, s46, 31
	s_waitcnt vmcnt(24)
	v_mul_f32_e32 v25, v60, v192
	v_mul_f32_e32 v62, v61, v193
	ds_write2_b32 v24, v25, v62 offset1:66
	v_pk_mul_f32 v[22:23], v[20:21], v[194:195]
	s_cbranch_execnz .LBB0_57

; __device__ __forceinline__ void transpose_item(const float* W, int ldw, int col0_src, bf16* WT, int K, int row0_dst, const float* gain, LAS float* scr, int k0, int lane) {
;     ...
; #pragma unroll
;     for (int i = 0; i < 32; ++i) { const int kk = 2 * i + (lane >> 5); float v = wv[i]; if (gain) v *= gain[k0 + kk]; scr[kk * 33 + (lane & 31)] = v; }
.LBB0_57:
	s_waitcnt vmcnt(21)
	v_add_u32_e32 v20, v28, v32
	s_and_b64 vcc, exec, s[4:5]
	ds_write2_b32 v20, v22, v23 offset1:66
	s_cbranch_vccnz .LBB0_74
	s_ashr_i32 s47, s46, 31
	s_waitcnt vmcnt(20)
	v_mul_f32_e32 v24, v58, v196
	v_mul_f32_e32 v25, v59, v197
	ds_write2_b32 v43, v24, v25 offset1:66
	v_pk_mul_f32 v[20:21], v[18:19], v[198:199]
	s_cbranch_execnz .LBB0_60

; __device__ __forceinline__ void transpose_item(const float* W, int ldw, int col0_src, bf16* WT, int K, int row0_dst, const float* gain, LAS float* scr, int k0, int lane) {
;     ...
; #pragma unroll
;     for (int i = 0; i < 32; ++i) { const int kk = 2 * i + (lane >> 5); float v = wv[i]; if (gain) v *= gain[k0 + kk]; scr[kk * 33 + (lane & 31)] = v; }
.LBB0_60:
	s_waitcnt vmcnt(17)
	v_add_u32_e32 v18, v28, v33
	ds_write2_b32 v18, v20, v21 offset1:66
	s_and_b64 vcc, exec, s[4:5]
	v_add_u32_e32 v20, v28, v34
	s_cbranch_vccnz .LBB0_75
	s_ashr_i32 s47, s46, 31
	s_waitcnt vmcnt(16)
	v_mul_f32_e32 v21, v56, v200
	v_mul_f32_e32 v24, v57, v201
	ds_write2_b32 v20, v21, v24 offset1:66
	v_pk_mul_f32 v[18:19], v[16:17], v[202:203]
	s_cbranch_execnz .LBB0_63

; __device__ __forceinline__ void transpose_item(const float* W, int ldw, int col0_src, bf16* WT, int K, int row0_dst, const float* gain, LAS float* scr, int k0, int lane) {
;     ...
; #pragma unroll
;     for (int i = 0; i < 32; ++i) { const int kk = 2 * i + (lane >> 5); float v = wv[i]; if (gain) v *= gain[k0 + kk]; scr[kk * 33 + (lane & 31)] = v; }
.LBB0_63:
	s_waitcnt vmcnt(16)
	ds_write2_b32 v44, v18, v19 offset1:66
	s_and_b64 vcc, exec, s[4:5]
	v_add_u32_e32 v18, v28, v35
	s_cbranch_vccnz .LBB0_76
	s_ashr_i32 s47, s46, 31
	s_waitcnt vmcnt(12)
	v_mul_f32_e32 v19, v54, v204
	v_mul_f32_e32 v22, v55, v205
	ds_write2_b32 v18, v19, v22 offset1:66
	v_pk_mul_f32 v[16:17], v[14:15], v[206:207]
	s_cbranch_execnz .LBB0_66

; __device__ __forceinline__ void transpose_item(const float* W, int ldw, int col0_src, bf16* WT, int K, int row0_dst, const float* gain, LAS float* scr, int k0, int lane) {
;     ...
; #pragma unroll
;     for (int i = 0; i < 32; ++i) { const int kk = 2 * i + (lane >> 5); float v = wv[i]; if (gain) v *= gain[k0 + kk]; scr[kk * 33 + (lane & 31)] = v; }
.LBB0_66:
	s_waitcnt vmcnt(12)
	ds_write2_b32 v18, v16, v17 offset0:132 offset1:198
	s_and_b64 vcc, exec, s[4:5]
	v_add_u32_e32 v16, 0x400, v18
	s_cbranch_vccnz .LBB0_77
	s_ashr_i32 s47, s46, 31
	s_waitcnt vmcnt(8)
	v_mul_f32_e32 v17, v52, v208
	v_mul_f32_e32 v19, v53, v209
	ds_write2_b32 v16, v17, v19 offset0:8 offset1:74
	v_pk_mul_f32 v[14:15], v[12:13], v[210:211]
	s_cbranch_execnz .LBB0_69

; __device__ __forceinline__ void transpose_item(const float* W, int ldw, int col0_src, bf16* WT, int K, int row0_dst, const float* gain, LAS float* scr, int k0, int lane) {
;     ...
; #pragma unroll
;     for (int i = 0; i < 32; ++i) { const int kk = 2 * i + (lane >> 5); float v = wv[i]; if (gain) v *= gain[k0 + kk]; scr[kk * 33 + (lane & 31)] = v; }
.LBB0_69:
	s_waitcnt vmcnt(8)
	ds_write2_b32 v16, v14, v15 offset0:140 offset1:206
	s_and_b64 vcc, exec, s[4:5]
	v_add_u32_e32 v14, 0x800, v18
	s_cbranch_vccnz .LBB0_78
	s_ashr_i32 s47, s46, 31
	s_waitcnt vmcnt(4)
	v_mul_f32_e32 v15, v9, v212
	v_mul_f32_e32 v18, v51, v213
	ds_write2_b32 v14, v15, v18 offset0:16 offset1:82
	v_pk_mul_f32 v[12:13], v[10:11], v[214:215]
	s_cbranch_execnz .LBB0_7
	s_branch .LBB0_6
